# norm0 phase: w_out transposes moved to workgroups 128..255 (which have one norm row fewer per wave) for balance
# baseline (speedup 1.0000x reference)
.LBB0_27:
	v_writelane_b32 v254, s2, 60
	s_cmp_lg_u32 s39, 1
	s_cbranch_scc1 .LBB0_36
	v_readlane_b32 s2, v254, 58
	v_readlane_b32 s3, v254, 59
	s_add_i32 s2, s2, s64
	s_addk_i32 s2, 0xfc00
	s_cmp_lt_i32 s2, 0
	s_cbranch_scc1 .LBB0_36
	v_readlane_b32 s24, v252, 11
	v_readlane_b32 s25, v252, 12
	s_load_dword s3, s[24:25], 0x0
	v_readlane_b32 s24, v254, 58
	v_readlane_b32 s25, v254, 59
	s_lshl_b32 s24, s24, 14
	s_waitcnt vmcnt(0)
	v_lshlrev_b32_e32 v0, 5, v244
	v_and_b32_e32 v7, 31, v182
	s_movk_i32 s25, 0x400
	s_add_i32 s24, s24, 0
	v_and_or_b32 v8, v0, s25, v7
	v_lshrrev_b32_e32 v0, 5, v244
	v_lshlrev_b32_e32 v1, 3, v244
	v_lshl_add_u32 v2, v7, 2, s24
	v_mul_u32_u24_e32 v3, 0x84, v0
	v_lshrrev_b32_e32 v9, 3, v244
	v_and_b32_e32 v4, 56, v1
	v_mul_u32_u24_e32 v1, 0x84, v4
	s_waitcnt lgkmcnt(0)
	v_lshlrev_b32_e32 v5, 2, v9
	v_add_u32_e32 v14, v2, v3
	s_waitcnt lgkmcnt(0)
	s_lshl_b32 s3, s3, 3
	v_add3_u32 v10, s24, v1, v5
	v_or_b32_e32 v11, 8, v9
	v_or_b32_e32 v12, 16, v9
	v_or_b32_e32 v13, 24, v9
	v_mov_b32_e32 v1, v0
	v_lshlrev_b32_e32 v4, 1, v4
	v_add_u32_e32 v15, 0x400, v14
	v_add_u32_e32 v16, 0x800, v14
	v_add_u32_e32 v17, 0xc00, v14
	v_add_u32_e32 v18, 0x1000, v14
	v_add_u32_e32 v19, 0x1400, v14
	v_add_u32_e32 v20, 0x1800, v14
	v_add_u32_e32 v21, 0x1c00, v14
	s_branch .LBB0_31
